# RWKV consumer waves at s_setprio 2 during the prompt loop so the loader/transposer waves do not take their issue slots
# baseline (speedup 1.0000x reference)
; #define LAS __attribute__((address_space(3)))
; #define GAS __attribute__((address_space(1)))
; #define R4_ISSUE(cc, slot) do { const GAS float* g_ = gp + (size_t)(cc) * 2048; LAS float* l_ = ring + (slot) * 1536; _Pragma("unroll") for (int i_ = 0; i_ < 6; ++i_) \
;         __builtin_amdgcn_global_load_lds((const GAS unsigned*)(g_ + off[i_]), (LAS unsigned*)(l_ + i_ * 256), 16, 0, 0); } while (0)
; __device__ __forceinline__ void rwkv_prompt_wave4(LAS float* ring, const GAS float* RW, int mbase, int h, int rq, GAS float* Sout, GAS float* YR, int lane) {
;     ...
;     for (int cc = 0; cc < 3; ++cc) R4_ISSUE(cc, cc);
;     float ykeep = 0.f;
;     R4Ops oA, oB, oC, oD;
;     asm volatile("s_waitcnt vmcnt(12)" ::: "memory");
;     R4_LOAD(oA, ring); R4_LOAD(oB, ring + 384);
;     for (int ci = 0; ci < NCH; ++ci) {
;         { const int cn = ci + 3; const int cl = cn < NCH ? cn : NCH - 1; R4_ISSUE(cl, cn % R4_NS); }
;         const LAS float* cb = ring + (ci % R4_NS) * 1536; const LAS float* nb = ring + ((ci + 1) % R4_NS) * 1536;
;         R4_LOAD(oC, cb + 768);  R4_STEP(oA, 0);
;         R4_LOAD(oD, cb + 1152); R4_STEP(oB, 1);
;         asm volatile("s_waitcnt vmcnt(12)" ::: "memory");
;         R4_LOAD(oA, nb);        R4_STEP(oC, 2);
;         R4_LOAD(oB, nb + 384);  R4_STEP(oD, 3);
;         if (cgp < 4) YR[(size_t)(mbase + ci * 4 + cgp) * 512 + h * 64 + rq * 4 + rl] = ykeep;
;     }
;     asm volatile("s_waitcnt vmcnt(0)" ::: "memory");
;     ...
;     *(GAS f32x4*)(Sout + (rq * 4 + rl) * 64 + cgp * 4) = (f32x4){S[0].x, S[0].y, S[1].x, S[1].y};
; __device__ __forceinline__ void m2_phase(ArgP A, int layer, LAS unsigned char* lds, int tid, int lane, int wave, int bid, int G) {
;     ...
;         if (wave < 4) for (int rr_ = 0; rr_ < REP_RWKV; ++rr_) for (int job = bid * 4 + wave; job < 512; job += Gh * 4) { const int b = job >> 7, h = (job >> 4) & 7, rq = job & 15;
;             rwkv_prompt_wave4((LAS float*)(lds + wave * 30720), RW, b * SEQ, h, rq, A->out + O_WKV_P + (((size_t)layer * 4 + b) * 8 + h) * 4096, YR, lane); }
.LBB0_704:
	s_ashr_i32 s1, s17, 31
	s_add_u32 s0, s17, s2
	s_addc_u32 s1, s1, 0
	s_lshl_b64 s[0:1], s[0:1], 17
	s_add_u32 s0, s12, s0
	s_addc_u32 s1, s13, s1
	s_lshl_b32 s10, s16, 14
	s_add_u32 s0, s0, s10
	s_addc_u32 s1, s1, 0
	s_waitcnt lgkmcnt(0)
	s_barrier
	s_setprio 0
	v_lshlrev_b32_e32 v0, 8, v59
	v_mov_b32_e32 v1, v17
	v_lshl_add_u64 v[0:1], s[0:1], 0, v[0:1]
	v_readlane_b32 s0, v252, 17
	s_waitcnt vmcnt(0)
	s_add_i32 s3, s3, s0
	v_readlane_b32 s0, v253, 29
	v_mov_b32_e32 v59, v17
	s_add_i32 s15, s15, s0
	v_lshl_add_u64 v[0:1], v[0:1], 0, v[58:59]
	s_cmpk_gt_i32 s3, 0x1ff
	global_store_dwordx4 v[0:1], v[42:45], off
	s_cbranch_scc1 .LBB0_709
.LBB0_705:
	s_lshl_b32 s0, s15, 2
	s_ashr_i32 s17, s3, 7
	s_and_b32 s24, s0, 0xf0
	s_lshl_b32 s0, s17, 11
	s_bfe_u32 s16, s3, 0x30004
	s_lshl_b32 s82, s16, 8
	s_mov_b32 s21, s83
	v_mov_b32_e32 v71, 0
	v_or_b32_e32 v62, s0, v236
	v_or_b32_e32 v70, s24, v52
	v_mov_b32_e32 v44, 0
	v_mov_b32_e32 v45, v71
	s_lshl_b32 s1, s3, 2
	s_and_b32 s1, s1, 60
	v_or_b32_e32 v59, s1, v65
	v_lshl_add_u32 v42, v59, 2, s14
	s_barrier
	ds_read_b128 v[26:29], v68 offset:1024
	ds_read_b128 v[4:7], v68 offset:256
	ds_read_b128 v[8:11], v68 offset:512
	ds_read_b32 v64, v42 offset:768
	ds_read_b128 v[22:25], v68 offset:1280
	ds_read_b128 v[0:3], v68
	ds_read_b128 v[38:41], v68 offset:2560
	ds_read_b128 v[18:21], v68 offset:1792
	ds_read_b128 v[30:33], v68 offset:2048
	ds_read_b32 v66, v42 offset:2304
	ds_read_b128 v[34:37], v68 offset:2816
	ds_read_b128 v[12:15], v68 offset:1536
	s_mov_b32 s21, 0
	s_mov_b32 s22, 0
	s_mov_b32 s23, 3
	s_movk_i32 s27, 0x1800
	v_mov_b32_e32 v46, v67
	v_mov_b32_e32 v47, v70
	v_mov_b32_e32 v42, 0
	v_mov_b32_e32 v43, v71
	s_waitcnt lgkmcnt(0)
	s_setprio 2
	s_branch .LBB0_707
